# GEMM K-loops: back edge rotated - next-iteration SALU bookkeeping moved before the loop-back barrier, exit path gets its own barrier copy
# baseline (speedup 1.0000x reference)
.Lmy_g1010_body:
	ds_read_b128 v[130:133], v152
	ds_read_b128 v[140:143], v152 offset:1024
	ds_read_b128 v[148:151], v152 offset:2048
	ds_read_b128 v[152:155], v152 offset:3072
	ds_read_b128 v[156:159], v168
	ds_read_b128 v[160:163], v168 offset:1024
	ds_read_b128 v[164:167], v168 offset:2048
	ds_read_b128 v[168:171], v168 offset:3072
	v_lshl_add_u64 v[192:193], s[36:37], 0, v[138:139]
	s_add_i32 m0, s13, 0xc000
	ds_read_b128 v[172:175], v147
	ds_read_b128 v[176:179], v147 offset:1024
	ds_read_b128 v[180:183], v147 offset:2048
	ds_read_b128 v[184:187], v147 offset:3072
	ds_read_b128 v[188:191], v147 offset:4096
	ds_read_b128 v[196:199], v147 offset:5120
	ds_read_b128 v[200:203], v147 offset:6144
	ds_read_b128 v[204:207], v147 offset:7168
	global_load_lds_dwordx4 v[192:193], off
	v_lshl_add_u64 v[192:193], s[36:37], 0, v[136:137]
	s_add_i32 m0, s13, 0xe000
	s_nop 0
	global_load_lds_dwordx4 v[192:193], off
	s_waitcnt vmcnt(8)
	s_waitcnt lgkmcnt(0)
	s_barrier
	s_setprio 1
	s_waitcnt lgkmcnt(0)
	v_mfma_f32_16x16x32_bf16 v[126:129], v[130:133], v[172:175], v[126:129]
	v_mfma_f32_16x16x32_bf16 v[94:97], v[148:151], v[172:175], v[94:97]
	v_mfma_f32_16x16x32_bf16 v[122:125], v[130:133], v[180:183], v[122:125]
	v_mfma_f32_16x16x32_bf16 v[90:93], v[148:151], v[180:183], v[90:93]
	v_mfma_f32_16x16x32_bf16 v[118:121], v[130:133], v[188:191], v[118:121]
	v_mfma_f32_16x16x32_bf16 v[86:89], v[148:151], v[188:191], v[86:89]
	v_mfma_f32_16x16x32_bf16 v[114:117], v[130:133], v[200:203], v[114:117]
	v_mfma_f32_16x16x32_bf16 v[82:85], v[148:151], v[200:203], v[82:85]
	v_mfma_f32_16x16x32_bf16 v[126:129], v[140:143], v[176:179], v[126:129]
	v_mfma_f32_16x16x32_bf16 v[94:97], v[152:155], v[176:179], v[94:97]
	v_mfma_f32_16x16x32_bf16 v[122:125], v[140:143], v[184:187], v[122:125]
	v_mfma_f32_16x16x32_bf16 v[90:93], v[152:155], v[184:187], v[90:93]
	v_mfma_f32_16x16x32_bf16 v[118:121], v[140:143], v[196:199], v[118:121]
	v_mfma_f32_16x16x32_bf16 v[86:89], v[152:155], v[196:199], v[86:89]
	v_mfma_f32_16x16x32_bf16 v[114:117], v[140:143], v[204:207], v[114:117]
	v_mfma_f32_16x16x32_bf16 v[82:85], v[152:155], v[204:207], v[82:85]
	s_setprio 0
	s_setprio 1
	v_mfma_f32_16x16x32_bf16 v[62:65], v[156:159], v[172:175], v[62:65]
	v_mfma_f32_16x16x32_bf16 v[30:33], v[164:167], v[172:175], v[30:33]
	v_mfma_f32_16x16x32_bf16 v[58:61], v[156:159], v[180:183], v[58:61]
	v_mfma_f32_16x16x32_bf16 v[26:29], v[164:167], v[180:183], v[26:29]
	v_mfma_f32_16x16x32_bf16 v[54:57], v[156:159], v[188:191], v[54:57]
	v_mfma_f32_16x16x32_bf16 v[22:25], v[164:167], v[188:191], v[22:25]
	v_mfma_f32_16x16x32_bf16 v[50:53], v[156:159], v[200:203], v[50:53]
	v_mfma_f32_16x16x32_bf16 v[18:21], v[164:167], v[200:203], v[18:21]
	v_mfma_f32_16x16x32_bf16 v[62:65], v[160:163], v[176:179], v[62:65]
	v_mfma_f32_16x16x32_bf16 v[30:33], v[168:171], v[176:179], v[30:33]
	v_mfma_f32_16x16x32_bf16 v[58:61], v[160:163], v[184:187], v[58:61]
	v_mfma_f32_16x16x32_bf16 v[26:29], v[168:171], v[184:187], v[26:29]
	v_mfma_f32_16x16x32_bf16 v[54:57], v[160:163], v[196:199], v[54:57]
	v_mfma_f32_16x16x32_bf16 v[22:25], v[168:171], v[196:199], v[22:25]
	v_mfma_f32_16x16x32_bf16 v[50:53], v[160:163], v[204:207], v[50:53]
	v_mfma_f32_16x16x32_bf16 v[18:21], v[168:171], v[204:207], v[18:21]
	s_setprio 0
	s_barrier
	s_add_i32 s69, s69, s3
	v_lshl_add_u64 v[192:193], s[66:67], 0, v[0:1]
	s_mov_b32 m0, s69
	ds_read_b128 v[172:175], v147 offset:16384
	ds_read_b128 v[176:179], v147 offset:17408
	ds_read_b128 v[180:183], v147 offset:18432
	ds_read_b128 v[184:187], v147 offset:19456
	ds_read_b128 v[188:191], v147 offset:20480
	ds_read_b128 v[196:199], v147 offset:21504
	ds_read_b128 v[200:203], v147 offset:22528
	ds_read_b128 v[204:207], v147 offset:23552
	global_load_lds_dwordx4 v[192:193], off
	s_add_i32 m0, s69, 0x2000
	v_lshl_add_u64 v[208:209], s[66:67], 0, v[134:135]
	s_add_u32 s66, s66, s18
	s_addc_u32 s67, s67, 0
	s_add_i32 s43, s43, s3
	global_load_lds_dwordx4 v[208:209], off
	v_lshl_add_u64 v[218:219], s[66:67], 0, v[0:1]
	s_mov_b32 m0, s43
	v_lshl_add_u64 v[220:221], s[66:67], 0, v[134:135]
	global_load_lds_dwordx4 v[218:219], off
	s_add_i32 m0, s43, 0x2000
	v_lshl_add_u64 v[222:223], s[38:39], 0, v[0:1]
	global_load_lds_dwordx4 v[220:221], off
	s_mov_b32 m0, s13
	v_lshl_add_u64 v[224:225], s[38:39], 0, v[134:135]
	global_load_lds_dwordx4 v[222:223], off
	s_mov_b32 m0, s23
	s_nop 0
	global_load_lds_dwordx4 v[224:225], off
	s_waitcnt vmcnt(8)
	s_waitcnt lgkmcnt(0)
	s_barrier
	s_setprio 1
	s_waitcnt lgkmcnt(0)
	v_mfma_f32_16x16x32_bf16 v[110:113], v[130:133], v[172:175], v[110:113]
	v_mfma_f32_16x16x32_bf16 v[78:81], v[148:151], v[172:175], v[78:81]
	v_mfma_f32_16x16x32_bf16 v[106:109], v[130:133], v[180:183], v[106:109]
	v_mfma_f32_16x16x32_bf16 v[74:77], v[148:151], v[180:183], v[74:77]
	v_mfma_f32_16x16x32_bf16 v[102:105], v[130:133], v[188:191], v[102:105]
	v_mfma_f32_16x16x32_bf16 v[70:73], v[148:151], v[188:191], v[70:73]
	v_mfma_f32_16x16x32_bf16 v[98:101], v[130:133], v[200:203], v[98:101]
	v_mfma_f32_16x16x32_bf16 v[66:69], v[148:151], v[200:203], v[66:69]
	v_mfma_f32_16x16x32_bf16 v[110:113], v[140:143], v[176:179], v[110:113]
	v_mfma_f32_16x16x32_bf16 v[78:81], v[152:155], v[176:179], v[78:81]
	v_mfma_f32_16x16x32_bf16 v[106:109], v[140:143], v[184:187], v[106:109]
	v_mfma_f32_16x16x32_bf16 v[74:77], v[152:155], v[184:187], v[74:77]
	v_mfma_f32_16x16x32_bf16 v[102:105], v[140:143], v[196:199], v[102:105]
	v_mfma_f32_16x16x32_bf16 v[70:73], v[152:155], v[196:199], v[70:73]
	v_mfma_f32_16x16x32_bf16 v[98:101], v[140:143], v[204:207], v[98:101]
	v_mfma_f32_16x16x32_bf16 v[66:69], v[152:155], v[204:207], v[66:69]
	s_setprio 0
	s_setprio 1
	v_mfma_f32_16x16x32_bf16 v[46:49], v[156:159], v[172:175], v[46:49]
	v_mfma_f32_16x16x32_bf16 v[14:17], v[164:167], v[172:175], v[14:17]
	v_mfma_f32_16x16x32_bf16 v[42:45], v[156:159], v[180:183], v[42:45]
	v_mfma_f32_16x16x32_bf16 v[10:13], v[164:167], v[180:183], v[10:13]
	v_mfma_f32_16x16x32_bf16 v[38:41], v[156:159], v[188:191], v[38:41]
	v_mfma_f32_16x16x32_bf16 v[6:9], v[164:167], v[188:191], v[6:9]
	v_mfma_f32_16x16x32_bf16 v[34:37], v[156:159], v[200:203], v[34:37]
	v_mfma_f32_16x16x32_bf16 v[2:5], v[164:167], v[200:203], v[2:5]
	v_mfma_f32_16x16x32_bf16 v[46:49], v[160:163], v[176:179], v[46:49]
	v_mfma_f32_16x16x32_bf16 v[14:17], v[168:171], v[176:179], v[14:17]
	v_mfma_f32_16x16x32_bf16 v[42:45], v[160:163], v[184:187], v[42:45]
	v_mfma_f32_16x16x32_bf16 v[10:13], v[168:171], v[184:187], v[10:13]
	v_mfma_f32_16x16x32_bf16 v[38:41], v[160:163], v[196:199], v[38:41]
	v_mfma_f32_16x16x32_bf16 v[6:9], v[168:171], v[196:199], v[6:9]
	v_mfma_f32_16x16x32_bf16 v[34:37], v[160:163], v[204:207], v[34:37]
	v_mfma_f32_16x16x32_bf16 v[2:5], v[168:171], v[204:207], v[2:5]
	s_setprio 0
	s_barrier
	s_add_i32 s43, 0, 0x18000
	s_add_i32 s66, 0, 0x1c000
	v_add_u32_e32 v152, s43, v145
	v_add_u32_e32 v168, s66, v145
	ds_read_b128 v[130:133], v152
	ds_read_b128 v[140:143], v152 offset:1024
	ds_read_b128 v[148:151], v152 offset:2048
	ds_read_b128 v[152:155], v152 offset:3072
	ds_read_b128 v[156:159], v168
	ds_read_b128 v[160:163], v168 offset:1024
	ds_read_b128 v[164:167], v168 offset:2048
	ds_read_b128 v[168:171], v168 offset:3072
	s_add_u32 s38, s38, s18
	s_addc_u32 s39, s39, 0
	s_mov_b32 m0, s44
	v_lshl_add_u64 v[226:227], s[38:39], 0, v[0:1]
	ds_read_b128 v[172:175], v147 offset:32768
	ds_read_b128 v[176:179], v147 offset:33792
	ds_read_b128 v[180:183], v147 offset:34816
	ds_read_b128 v[184:187], v147 offset:35840
	ds_read_b128 v[188:191], v147 offset:36864
	ds_read_b128 v[196:199], v147 offset:37888
	ds_read_b128 v[200:203], v147 offset:38912
	ds_read_b128 v[204:207], v147 offset:39936
	global_load_lds_dwordx4 v[226:227], off
	v_lshl_add_u64 v[226:227], s[38:39], 0, v[134:135]
	s_mov_b32 m0, s45
	s_nop 0
	global_load_lds_dwordx4 v[226:227], off
	s_waitcnt vmcnt(8)
	s_waitcnt lgkmcnt(0)
	s_barrier
	s_setprio 1
	s_waitcnt lgkmcnt(0)
	v_mfma_f32_16x16x32_bf16 v[126:129], v[130:133], v[172:175], v[126:129]
	v_mfma_f32_16x16x32_bf16 v[94:97], v[148:151], v[172:175], v[94:97]
	v_mfma_f32_16x16x32_bf16 v[122:125], v[130:133], v[180:183], v[122:125]
	v_mfma_f32_16x16x32_bf16 v[90:93], v[148:151], v[180:183], v[90:93]
	v_mfma_f32_16x16x32_bf16 v[118:121], v[130:133], v[188:191], v[118:121]
	v_mfma_f32_16x16x32_bf16 v[86:89], v[148:151], v[188:191], v[86:89]
	v_mfma_f32_16x16x32_bf16 v[114:117], v[130:133], v[200:203], v[114:117]
	v_mfma_f32_16x16x32_bf16 v[82:85], v[148:151], v[200:203], v[82:85]
	v_mfma_f32_16x16x32_bf16 v[126:129], v[140:143], v[176:179], v[126:129]
	v_mfma_f32_16x16x32_bf16 v[94:97], v[152:155], v[176:179], v[94:97]
	v_mfma_f32_16x16x32_bf16 v[122:125], v[140:143], v[184:187], v[122:125]
	v_mfma_f32_16x16x32_bf16 v[90:93], v[152:155], v[184:187], v[90:93]
	v_mfma_f32_16x16x32_bf16 v[118:121], v[140:143], v[196:199], v[118:121]
	v_mfma_f32_16x16x32_bf16 v[86:89], v[152:155], v[196:199], v[86:89]
	v_mfma_f32_16x16x32_bf16 v[114:117], v[140:143], v[204:207], v[114:117]
	v_mfma_f32_16x16x32_bf16 v[82:85], v[152:155], v[204:207], v[82:85]
	s_setprio 0
	s_setprio 1
	v_mfma_f32_16x16x32_bf16 v[62:65], v[156:159], v[172:175], v[62:65]
	v_mfma_f32_16x16x32_bf16 v[30:33], v[164:167], v[172:175], v[30:33]
	v_mfma_f32_16x16x32_bf16 v[58:61], v[156:159], v[180:183], v[58:61]
	v_mfma_f32_16x16x32_bf16 v[26:29], v[164:167], v[180:183], v[26:29]
	v_mfma_f32_16x16x32_bf16 v[54:57], v[156:159], v[188:191], v[54:57]
	v_mfma_f32_16x16x32_bf16 v[22:25], v[164:167], v[188:191], v[22:25]
	v_mfma_f32_16x16x32_bf16 v[50:53], v[156:159], v[200:203], v[50:53]
	v_mfma_f32_16x16x32_bf16 v[18:21], v[164:167], v[200:203], v[18:21]
	v_mfma_f32_16x16x32_bf16 v[62:65], v[160:163], v[176:179], v[62:65]
	v_mfma_f32_16x16x32_bf16 v[30:33], v[168:171], v[176:179], v[30:33]
	v_mfma_f32_16x16x32_bf16 v[58:61], v[160:163], v[184:187], v[58:61]
	v_mfma_f32_16x16x32_bf16 v[26:29], v[168:171], v[184:187], v[26:29]
	v_mfma_f32_16x16x32_bf16 v[54:57], v[160:163], v[196:199], v[54:57]
	v_mfma_f32_16x16x32_bf16 v[22:25], v[168:171], v[196:199], v[22:25]
	v_mfma_f32_16x16x32_bf16 v[50:53], v[160:163], v[204:207], v[50:53]
	v_mfma_f32_16x16x32_bf16 v[18:21], v[168:171], v[204:207], v[18:21]
	s_setprio 0
	s_barrier
	s_add_i32 s38, s43, s3
	v_lshl_add_u64 v[192:193], v[192:193], 0, s[88:89]
	s_mov_b32 m0, s38
	ds_read_b128 v[172:175], v147 offset:49152
	ds_read_b128 v[176:179], v147 offset:50176
	ds_read_b128 v[180:183], v147 offset:51200
	ds_read_b128 v[184:187], v147 offset:52224
	ds_read_b128 v[188:191], v147 offset:53248
	ds_read_b128 v[196:199], v147 offset:54272
	ds_read_b128 v[200:203], v147 offset:55296
	ds_read_b128 v[204:207], v147 offset:56320
	global_load_lds_dwordx4 v[192:193], off
	v_lshl_add_u64 v[192:193], v[208:209], 0, s[88:89]
	s_add_i32 m0, s38, 0x2000
	s_add_i32 s38, s66, s3
	global_load_lds_dwordx4 v[192:193], off
	v_lshl_add_u64 v[192:193], v[218:219], 0, s[88:89]
	s_mov_b32 m0, s38
	s_nop 0
	global_load_lds_dwordx4 v[192:193], off
	v_lshl_add_u64 v[192:193], v[220:221], 0, s[88:89]
	s_add_i32 m0, s38, 0x2000
	s_nop 0
	global_load_lds_dwordx4 v[192:193], off
	v_lshl_add_u64 v[192:193], v[222:223], 0, s[88:89]
	s_mov_b32 m0, s52
	s_nop 0
	global_load_lds_dwordx4 v[192:193], off
	v_lshl_add_u64 v[192:193], v[224:225], 0, s[88:89]
	s_mov_b32 m0, s53
	s_nop 0
	global_load_lds_dwordx4 v[192:193], off
	s_waitcnt vmcnt(8)
	s_waitcnt lgkmcnt(0)
	s_barrier
	s_setprio 1
	s_waitcnt lgkmcnt(0)
	v_mfma_f32_16x16x32_bf16 v[110:113], v[130:133], v[172:175], v[110:113]
	v_mfma_f32_16x16x32_bf16 v[78:81], v[148:151], v[172:175], v[78:81]
	v_mfma_f32_16x16x32_bf16 v[106:109], v[130:133], v[180:183], v[106:109]
	v_mfma_f32_16x16x32_bf16 v[74:77], v[148:151], v[180:183], v[74:77]
	v_mfma_f32_16x16x32_bf16 v[102:105], v[130:133], v[188:191], v[102:105]
	v_mfma_f32_16x16x32_bf16 v[70:73], v[148:151], v[188:191], v[70:73]
	v_mfma_f32_16x16x32_bf16 v[98:101], v[130:133], v[200:203], v[98:101]
	v_mfma_f32_16x16x32_bf16 v[66:69], v[148:151], v[200:203], v[66:69]
	v_mfma_f32_16x16x32_bf16 v[110:113], v[140:143], v[176:179], v[110:113]
	v_mfma_f32_16x16x32_bf16 v[78:81], v[152:155], v[176:179], v[78:81]
	v_mfma_f32_16x16x32_bf16 v[106:109], v[140:143], v[184:187], v[106:109]
	v_mfma_f32_16x16x32_bf16 v[74:77], v[152:155], v[184:187], v[74:77]
	v_mfma_f32_16x16x32_bf16 v[102:105], v[140:143], v[196:199], v[102:105]
	v_mfma_f32_16x16x32_bf16 v[70:73], v[152:155], v[196:199], v[70:73]
	v_mfma_f32_16x16x32_bf16 v[98:101], v[140:143], v[204:207], v[98:101]
	v_mfma_f32_16x16x32_bf16 v[66:69], v[152:155], v[204:207], v[66:69]
	s_setprio 0
	s_setprio 1
	v_mfma_f32_16x16x32_bf16 v[46:49], v[156:159], v[172:175], v[46:49]
	v_mfma_f32_16x16x32_bf16 v[14:17], v[164:167], v[172:175], v[14:17]
	v_mfma_f32_16x16x32_bf16 v[42:45], v[156:159], v[180:183], v[42:45]
	v_mfma_f32_16x16x32_bf16 v[10:13], v[164:167], v[180:183], v[10:13]
	v_mfma_f32_16x16x32_bf16 v[38:41], v[156:159], v[188:191], v[38:41]
	v_mfma_f32_16x16x32_bf16 v[6:9], v[164:167], v[188:191], v[6:9]
	v_mfma_f32_16x16x32_bf16 v[34:37], v[156:159], v[200:203], v[34:37]
	v_mfma_f32_16x16x32_bf16 v[2:5], v[164:167], v[200:203], v[2:5]
	v_mfma_f32_16x16x32_bf16 v[46:49], v[160:163], v[176:179], v[46:49]
	v_mfma_f32_16x16x32_bf16 v[14:17], v[168:171], v[176:179], v[14:17]
	v_mfma_f32_16x16x32_bf16 v[42:45], v[160:163], v[184:187], v[42:45]
	v_mfma_f32_16x16x32_bf16 v[10:13], v[168:171], v[184:187], v[10:13]
	v_mfma_f32_16x16x32_bf16 v[38:41], v[160:163], v[196:199], v[38:41]
	v_mfma_f32_16x16x32_bf16 v[6:9], v[168:171], v[196:199], v[6:9]
	v_mfma_f32_16x16x32_bf16 v[34:37], v[160:163], v[204:207], v[34:37]
	v_mfma_f32_16x16x32_bf16 v[2:5], v[168:171], v[204:207], v[2:5]
	s_setprio 0
	s_add_u32 s16, s16, 0x100
	s_addc_u32 s17, s17, 0
	s_add_u32 s36, s36, 0x100
	s_addc_u32 s37, s37, 0
	s_cmp_ge_u32 s42, s51
	s_mov_b32 s38, s42
	s_cbranch_scc1 .Lmy_g1010_exit
	s_add_i32 s42, s38, 2
	s_add_u32 s43, s36, 0x80
	s_addc_u32 s39, s37, 0
	s_add_i32 s69, 0, 0x10000
	s_cmp_eq_u32 s55, s38
	s_cselect_b32 s39, s31, s39
	s_cselect_b32 s38, s30, s43
	s_cselect_b32 s67, s35, s17
	s_cselect_b32 s66, s34, s16
	s_add_i32 s43, 0, 0x14000
	v_add_u32_e32 v152, s69, v145
	v_add_u32_e32 v168, s43, v145
	s_barrier
	s_branch .Lmy_g1010_body
.Lmy_g1010_exit:
	s_barrier
	s_nop 0
	s_nop 0
	s_nop 0
	s_nop 0
	s_nop 0
	s_nop 0
	s_nop 0
	s_nop 0
	s_nop 0
	s_nop 0
	s_nop 0
	s_nop 0
	s_nop 0
	s_nop 0
	s_nop 0

.Lmy_g1187_body:
	ds_read_b128 v[144:147], v0
	ds_read_b128 v[148:151], v0 offset:1024
	ds_read_b128 v[152:155], v0 offset:2048
	ds_read_b128 v[156:159], v0 offset:3072
	v_add_u32_e32 v0, s17, v175
	ds_read_b128 v[160:163], v0
	ds_read_b128 v[178:181], v0 offset:1024
	ds_read_b128 v[182:185], v0 offset:2048
	ds_read_b128 v[186:189], v0 offset:3072
	v_lshl_add_u64 v[208:209], s[18:19], 0, v[142:143]
	s_add_i32 m0, s29, 0xc000
	ds_read_b128 v[190:193], v176
	ds_read_b128 v[196:199], v176 offset:1024
	ds_read_b128 v[200:203], v176 offset:2048
	ds_read_b128 v[204:207], v176 offset:3072
	ds_read_b128 v[218:221], v176 offset:4096
	ds_read_b128 v[222:225], v176 offset:5120
	ds_read_b128 v[226:229], v176 offset:6144
	ds_read_b128 v[230:233], v176 offset:7168
	global_load_lds_dwordx4 v[208:209], off
	v_lshl_add_u64 v[208:209], s[18:19], 0, v[140:141]
	s_add_i32 m0, s29, 0xe000
	s_nop 0
	global_load_lds_dwordx4 v[208:209], off
	s_waitcnt vmcnt(8)
	s_waitcnt lgkmcnt(0)
	s_barrier
	s_setprio 1
	s_waitcnt lgkmcnt(0)
	v_mfma_f32_16x16x32_bf16 v[126:129], v[144:147], v[190:193], v[126:129]
	v_mfma_f32_16x16x32_bf16 v[122:125], v[152:155], v[190:193], v[122:125]
	v_mfma_f32_16x16x32_bf16 v[110:113], v[144:147], v[200:203], v[110:113]
	v_mfma_f32_16x16x32_bf16 v[106:109], v[152:155], v[200:203], v[106:109]
	v_mfma_f32_16x16x32_bf16 v[94:97], v[144:147], v[218:221], v[94:97]
	v_mfma_f32_16x16x32_bf16 v[90:93], v[152:155], v[218:221], v[90:93]
	v_mfma_f32_16x16x32_bf16 v[78:81], v[144:147], v[226:229], v[78:81]
	v_mfma_f32_16x16x32_bf16 v[74:77], v[152:155], v[226:229], v[74:77]
	v_mfma_f32_16x16x32_bf16 v[126:129], v[148:151], v[196:199], v[126:129]
	v_mfma_f32_16x16x32_bf16 v[122:125], v[156:159], v[196:199], v[122:125]
	v_mfma_f32_16x16x32_bf16 v[110:113], v[148:151], v[204:207], v[110:113]
	v_mfma_f32_16x16x32_bf16 v[106:109], v[156:159], v[204:207], v[106:109]
	v_mfma_f32_16x16x32_bf16 v[94:97], v[148:151], v[222:225], v[94:97]
	v_mfma_f32_16x16x32_bf16 v[90:93], v[156:159], v[222:225], v[90:93]
	v_mfma_f32_16x16x32_bf16 v[78:81], v[148:151], v[230:233], v[78:81]
	v_mfma_f32_16x16x32_bf16 v[74:77], v[156:159], v[230:233], v[74:77]
	s_setprio 0
	s_setprio 1
	v_mfma_f32_16x16x32_bf16 v[118:121], v[160:163], v[190:193], v[118:121]
	v_mfma_f32_16x16x32_bf16 v[114:117], v[182:185], v[190:193], v[114:117]
	v_mfma_f32_16x16x32_bf16 v[102:105], v[160:163], v[200:203], v[102:105]
	v_mfma_f32_16x16x32_bf16 v[98:101], v[182:185], v[200:203], v[98:101]
	v_mfma_f32_16x16x32_bf16 v[86:89], v[160:163], v[218:221], v[86:89]
	v_mfma_f32_16x16x32_bf16 v[82:85], v[182:185], v[218:221], v[82:85]
	v_mfma_f32_16x16x32_bf16 v[70:73], v[160:163], v[226:229], v[70:73]
	v_mfma_f32_16x16x32_bf16 v[66:69], v[182:185], v[226:229], v[66:69]
	v_mfma_f32_16x16x32_bf16 v[118:121], v[178:181], v[196:199], v[118:121]
	v_mfma_f32_16x16x32_bf16 v[114:117], v[186:189], v[196:199], v[114:117]
	v_mfma_f32_16x16x32_bf16 v[102:105], v[178:181], v[204:207], v[102:105]
	v_mfma_f32_16x16x32_bf16 v[98:101], v[186:189], v[204:207], v[98:101]
	v_mfma_f32_16x16x32_bf16 v[86:89], v[178:181], v[222:225], v[86:89]
	v_mfma_f32_16x16x32_bf16 v[82:85], v[186:189], v[222:225], v[82:85]
	v_mfma_f32_16x16x32_bf16 v[70:73], v[178:181], v[230:233], v[70:73]
	v_mfma_f32_16x16x32_bf16 v[66:69], v[186:189], v[230:233], v[66:69]
	s_setprio 0
	s_barrier
	s_add_i32 s63, s63, s28
	v_lshl_add_u64 v[208:209], s[66:67], 0, v[132:133]
	s_mov_b32 m0, s63
	ds_read_b128 v[190:193], v176 offset:16384
	ds_read_b128 v[196:199], v176 offset:17408
	ds_read_b128 v[200:203], v176 offset:18432
	ds_read_b128 v[204:207], v176 offset:19456
	ds_read_b128 v[218:221], v176 offset:20480
	ds_read_b128 v[222:225], v176 offset:21504
	ds_read_b128 v[226:229], v176 offset:22528
	ds_read_b128 v[230:233], v176 offset:23552
	global_load_lds_dwordx4 v[208:209], off
	s_add_i32 m0, s63, 0x2000
	v_lshl_add_u64 v[234:235], s[66:67], 0, v[136:137]
	s_add_u32 s66, s66, s55
	s_addc_u32 s67, s67, 0
	s_add_i32 s17, s17, s28
	global_load_lds_dwordx4 v[234:235], off
	v_lshl_add_u64 v[242:243], s[66:67], 0, v[132:133]
	s_mov_b32 m0, s17
	v_lshl_add_u64 v[244:245], s[66:67], 0, v[136:137]
	global_load_lds_dwordx4 v[242:243], off
	s_add_i32 m0, s17, 0x2000
	v_lshl_add_u64 v[246:247], s[44:45], 0, v[130:131]
	global_load_lds_dwordx4 v[244:245], off
	s_mov_b32 m0, s29
	v_lshl_add_u64 v[248:249], s[44:45], 0, v[134:135]
	global_load_lds_dwordx4 v[246:247], off
	s_mov_b32 m0, s26
	s_nop 0
	global_load_lds_dwordx4 v[248:249], off
	s_waitcnt vmcnt(8)
	s_waitcnt lgkmcnt(0)
	s_barrier
	s_setprio 1
	s_waitcnt lgkmcnt(0)
	v_mfma_f32_16x16x32_bf16 v[62:65], v[144:147], v[190:193], v[62:65]
	v_mfma_f32_16x16x32_bf16 v[58:61], v[152:155], v[190:193], v[58:61]
	v_mfma_f32_16x16x32_bf16 v[46:49], v[144:147], v[200:203], v[46:49]
	v_mfma_f32_16x16x32_bf16 v[42:45], v[152:155], v[200:203], v[42:45]
	v_mfma_f32_16x16x32_bf16 v[30:33], v[144:147], v[218:221], v[30:33]
	v_mfma_f32_16x16x32_bf16 v[26:29], v[152:155], v[218:221], v[26:29]
	v_mfma_f32_16x16x32_bf16 v[14:17], v[144:147], v[226:229], v[14:17]
	v_mfma_f32_16x16x32_bf16 v[10:13], v[152:155], v[226:229], v[10:13]
	v_mfma_f32_16x16x32_bf16 v[62:65], v[148:151], v[196:199], v[62:65]
	v_mfma_f32_16x16x32_bf16 v[58:61], v[156:159], v[196:199], v[58:61]
	v_mfma_f32_16x16x32_bf16 v[46:49], v[148:151], v[204:207], v[46:49]
	v_mfma_f32_16x16x32_bf16 v[42:45], v[156:159], v[204:207], v[42:45]
	v_mfma_f32_16x16x32_bf16 v[30:33], v[148:151], v[222:225], v[30:33]
	v_mfma_f32_16x16x32_bf16 v[26:29], v[156:159], v[222:225], v[26:29]
	v_mfma_f32_16x16x32_bf16 v[14:17], v[148:151], v[230:233], v[14:17]
	v_mfma_f32_16x16x32_bf16 v[10:13], v[156:159], v[230:233], v[10:13]
	s_setprio 0
	s_setprio 1
	v_mfma_f32_16x16x32_bf16 v[54:57], v[160:163], v[190:193], v[54:57]
	v_mfma_f32_16x16x32_bf16 v[50:53], v[182:185], v[190:193], v[50:53]
	v_mfma_f32_16x16x32_bf16 v[38:41], v[160:163], v[200:203], v[38:41]
	v_mfma_f32_16x16x32_bf16 v[34:37], v[182:185], v[200:203], v[34:37]
	v_mfma_f32_16x16x32_bf16 v[22:25], v[160:163], v[218:221], v[22:25]
	v_mfma_f32_16x16x32_bf16 v[18:21], v[182:185], v[218:221], v[18:21]
	v_mfma_f32_16x16x32_bf16 v[6:9], v[160:163], v[226:229], v[6:9]
	v_mfma_f32_16x16x32_bf16 v[2:5], v[182:185], v[226:229], v[2:5]
	v_mfma_f32_16x16x32_bf16 v[54:57], v[178:181], v[196:199], v[54:57]
	v_mfma_f32_16x16x32_bf16 v[50:53], v[186:189], v[196:199], v[50:53]
	v_mfma_f32_16x16x32_bf16 v[38:41], v[178:181], v[204:207], v[38:41]
	v_mfma_f32_16x16x32_bf16 v[34:37], v[186:189], v[204:207], v[34:37]
	v_mfma_f32_16x16x32_bf16 v[22:25], v[178:181], v[222:225], v[22:25]
	v_mfma_f32_16x16x32_bf16 v[18:21], v[186:189], v[222:225], v[18:21]
	v_mfma_f32_16x16x32_bf16 v[6:9], v[178:181], v[230:233], v[6:9]
	v_mfma_f32_16x16x32_bf16 v[2:5], v[186:189], v[230:233], v[2:5]
	s_setprio 0
	s_barrier
	s_add_i32 s17, 0, 0x18000
	v_add_u32_e32 v0, s17, v175
	s_add_i32 s63, 0, 0x1c000
	ds_read_b128 v[144:147], v0
	ds_read_b128 v[148:151], v0 offset:1024
	ds_read_b128 v[152:155], v0 offset:2048
	ds_read_b128 v[156:159], v0 offset:3072
	v_add_u32_e32 v0, s63, v175
	ds_read_b128 v[160:163], v0
	ds_read_b128 v[178:181], v0 offset:1024
	ds_read_b128 v[182:185], v0 offset:2048
	ds_read_b128 v[186:189], v0 offset:3072
	s_add_u32 s44, s44, s34
	s_addc_u32 s45, s45, 0
	s_mov_b32 m0, s27
	v_lshl_add_u64 v[250:251], s[44:45], 0, v[130:131]
	ds_read_b128 v[190:193], v176 offset:32768
	ds_read_b128 v[196:199], v176 offset:33792
	ds_read_b128 v[200:203], v176 offset:34816
	ds_read_b128 v[204:207], v176 offset:35840
	ds_read_b128 v[218:221], v176 offset:36864
	ds_read_b128 v[222:225], v176 offset:37888
	ds_read_b128 v[226:229], v176 offset:38912
	ds_read_b128 v[230:233], v176 offset:39936
	global_load_lds_dwordx4 v[250:251], off
	v_lshl_add_u64 v[250:251], s[44:45], 0, v[134:135]
	s_mov_b32 m0, s8
	s_nop 0
	global_load_lds_dwordx4 v[250:251], off
	s_waitcnt vmcnt(8)
	s_waitcnt lgkmcnt(0)
	s_barrier
	s_setprio 1
	s_waitcnt lgkmcnt(0)
	v_mfma_f32_16x16x32_bf16 v[126:129], v[144:147], v[190:193], v[126:129]
	v_mfma_f32_16x16x32_bf16 v[122:125], v[152:155], v[190:193], v[122:125]
	v_mfma_f32_16x16x32_bf16 v[110:113], v[144:147], v[200:203], v[110:113]
	v_mfma_f32_16x16x32_bf16 v[106:109], v[152:155], v[200:203], v[106:109]
	v_mfma_f32_16x16x32_bf16 v[94:97], v[144:147], v[218:221], v[94:97]
	v_mfma_f32_16x16x32_bf16 v[90:93], v[152:155], v[218:221], v[90:93]
	v_mfma_f32_16x16x32_bf16 v[78:81], v[144:147], v[226:229], v[78:81]
	v_mfma_f32_16x16x32_bf16 v[74:77], v[152:155], v[226:229], v[74:77]
	v_mfma_f32_16x16x32_bf16 v[126:129], v[148:151], v[196:199], v[126:129]
	v_mfma_f32_16x16x32_bf16 v[122:125], v[156:159], v[196:199], v[122:125]
	v_mfma_f32_16x16x32_bf16 v[110:113], v[148:151], v[204:207], v[110:113]
	v_mfma_f32_16x16x32_bf16 v[106:109], v[156:159], v[204:207], v[106:109]
	v_mfma_f32_16x16x32_bf16 v[94:97], v[148:151], v[222:225], v[94:97]
	v_mfma_f32_16x16x32_bf16 v[90:93], v[156:159], v[222:225], v[90:93]
	v_mfma_f32_16x16x32_bf16 v[78:81], v[148:151], v[230:233], v[78:81]
	v_mfma_f32_16x16x32_bf16 v[74:77], v[156:159], v[230:233], v[74:77]
	s_setprio 0
	s_setprio 1
	v_mfma_f32_16x16x32_bf16 v[118:121], v[160:163], v[190:193], v[118:121]
	v_mfma_f32_16x16x32_bf16 v[114:117], v[182:185], v[190:193], v[114:117]
	v_mfma_f32_16x16x32_bf16 v[102:105], v[160:163], v[200:203], v[102:105]
	v_mfma_f32_16x16x32_bf16 v[98:101], v[182:185], v[200:203], v[98:101]
	v_mfma_f32_16x16x32_bf16 v[86:89], v[160:163], v[218:221], v[86:89]
	v_mfma_f32_16x16x32_bf16 v[82:85], v[182:185], v[218:221], v[82:85]
	v_mfma_f32_16x16x32_bf16 v[70:73], v[160:163], v[226:229], v[70:73]
	v_mfma_f32_16x16x32_bf16 v[66:69], v[182:185], v[226:229], v[66:69]
	v_mfma_f32_16x16x32_bf16 v[118:121], v[178:181], v[196:199], v[118:121]
	v_mfma_f32_16x16x32_bf16 v[114:117], v[186:189], v[196:199], v[114:117]
	v_mfma_f32_16x16x32_bf16 v[102:105], v[178:181], v[204:207], v[102:105]
	v_mfma_f32_16x16x32_bf16 v[98:101], v[186:189], v[204:207], v[98:101]
	v_mfma_f32_16x16x32_bf16 v[86:89], v[178:181], v[222:225], v[86:89]
	v_mfma_f32_16x16x32_bf16 v[82:85], v[186:189], v[222:225], v[82:85]
	v_mfma_f32_16x16x32_bf16 v[70:73], v[178:181], v[230:233], v[70:73]
	v_mfma_f32_16x16x32_bf16 v[66:69], v[186:189], v[230:233], v[66:69]
	s_setprio 0
	s_barrier
	s_add_i32 s17, s17, s28
	v_lshl_add_u64 v[208:209], v[208:209], 0, s[88:89]
	s_mov_b32 m0, s17
	ds_read_b128 v[190:193], v176 offset:49152
	ds_read_b128 v[196:199], v176 offset:50176
	ds_read_b128 v[200:203], v176 offset:51200
	ds_read_b128 v[204:207], v176 offset:52224
	ds_read_b128 v[218:221], v176 offset:53248
	ds_read_b128 v[222:225], v176 offset:54272
	ds_read_b128 v[226:229], v176 offset:55296
	ds_read_b128 v[230:233], v176 offset:56320
	global_load_lds_dwordx4 v[208:209], off
	v_lshl_add_u64 v[208:209], v[234:235], 0, s[88:89]
	s_add_i32 m0, s17, 0x2000
	s_add_i32 s17, s63, s28
	global_load_lds_dwordx4 v[208:209], off
	v_lshl_add_u64 v[208:209], v[242:243], 0, s[88:89]
	s_mov_b32 m0, s17
	s_nop 0
	global_load_lds_dwordx4 v[208:209], off
	v_lshl_add_u64 v[208:209], v[244:245], 0, s[88:89]
	s_add_i32 m0, s17, 0x2000
	s_nop 0
	global_load_lds_dwordx4 v[208:209], off
	v_lshl_add_u64 v[208:209], v[246:247], 0, s[88:89]
	s_mov_b32 m0, s10
	s_nop 0
	global_load_lds_dwordx4 v[208:209], off
	v_lshl_add_u64 v[208:209], v[248:249], 0, s[88:89]
	s_mov_b32 m0, s11
	s_nop 0
	global_load_lds_dwordx4 v[208:209], off
	s_waitcnt vmcnt(8)
	s_waitcnt lgkmcnt(0)
	s_barrier
	s_setprio 1
	s_waitcnt lgkmcnt(0)
	v_mfma_f32_16x16x32_bf16 v[62:65], v[144:147], v[190:193], v[62:65]
	v_mfma_f32_16x16x32_bf16 v[58:61], v[152:155], v[190:193], v[58:61]
	v_mfma_f32_16x16x32_bf16 v[46:49], v[144:147], v[200:203], v[46:49]
	v_mfma_f32_16x16x32_bf16 v[42:45], v[152:155], v[200:203], v[42:45]
	v_mfma_f32_16x16x32_bf16 v[30:33], v[144:147], v[218:221], v[30:33]
	v_mfma_f32_16x16x32_bf16 v[26:29], v[152:155], v[218:221], v[26:29]
	v_mfma_f32_16x16x32_bf16 v[14:17], v[144:147], v[226:229], v[14:17]
	v_mfma_f32_16x16x32_bf16 v[10:13], v[152:155], v[226:229], v[10:13]
	v_mfma_f32_16x16x32_bf16 v[62:65], v[148:151], v[196:199], v[62:65]
	v_mfma_f32_16x16x32_bf16 v[58:61], v[156:159], v[196:199], v[58:61]
	v_mfma_f32_16x16x32_bf16 v[46:49], v[148:151], v[204:207], v[46:49]
	v_mfma_f32_16x16x32_bf16 v[42:45], v[156:159], v[204:207], v[42:45]
	v_mfma_f32_16x16x32_bf16 v[30:33], v[148:151], v[222:225], v[30:33]
	v_mfma_f32_16x16x32_bf16 v[26:29], v[156:159], v[222:225], v[26:29]
	v_mfma_f32_16x16x32_bf16 v[14:17], v[148:151], v[230:233], v[14:17]
	v_mfma_f32_16x16x32_bf16 v[10:13], v[156:159], v[230:233], v[10:13]
	s_setprio 0
	s_setprio 1
	v_mfma_f32_16x16x32_bf16 v[54:57], v[160:163], v[190:193], v[54:57]
	v_mfma_f32_16x16x32_bf16 v[50:53], v[182:185], v[190:193], v[50:53]
	v_mfma_f32_16x16x32_bf16 v[38:41], v[160:163], v[200:203], v[38:41]
	v_mfma_f32_16x16x32_bf16 v[34:37], v[182:185], v[200:203], v[34:37]
	v_mfma_f32_16x16x32_bf16 v[22:25], v[160:163], v[218:221], v[22:25]
	v_mfma_f32_16x16x32_bf16 v[18:21], v[182:185], v[218:221], v[18:21]
	v_mfma_f32_16x16x32_bf16 v[6:9], v[160:163], v[226:229], v[6:9]
	v_mfma_f32_16x16x32_bf16 v[2:5], v[182:185], v[226:229], v[2:5]
	v_mfma_f32_16x16x32_bf16 v[54:57], v[178:181], v[196:199], v[54:57]
	v_mfma_f32_16x16x32_bf16 v[50:53], v[186:189], v[196:199], v[50:53]
	v_mfma_f32_16x16x32_bf16 v[38:41], v[178:181], v[204:207], v[38:41]
	v_mfma_f32_16x16x32_bf16 v[34:37], v[186:189], v[204:207], v[34:37]
	v_mfma_f32_16x16x32_bf16 v[22:25], v[178:181], v[222:225], v[22:25]
	v_mfma_f32_16x16x32_bf16 v[18:21], v[186:189], v[222:225], v[18:21]
	v_mfma_f32_16x16x32_bf16 v[6:9], v[178:181], v[230:233], v[6:9]
	v_mfma_f32_16x16x32_bf16 v[2:5], v[186:189], v[230:233], v[2:5]
	s_setprio 0
	s_add_u32 s5, s5, 0x100
	s_addc_u32 s16, s16, 0
	s_add_u32 s18, s18, 0x100
	s_addc_u32 s19, s19, 0
	s_cmp_ge_u32 s35, s12
	s_mov_b32 s17, s35
	s_cbranch_scc1 .Lmy_g1187_exit
	s_add_i32 s35, s17, 2
	s_add_u32 s44, s18, 0x80
	s_addc_u32 s45, s19, 0
	s_add_i32 s63, 0, 0x10000
	s_cmp_eq_u32 s9, s17
	s_cselect_b32 s45, s7, s45
	s_cselect_b32 s44, s6, s44
	v_add_u32_e32 v0, s63, v175
	s_cselect_b32 s67, s15, s16
	s_cselect_b32 s66, s14, s5
	s_add_i32 s17, 0, 0x14000
	s_barrier
	s_branch .Lmy_g1187_body
